# final_ln last phase: loop-invariant LN gamma/beta loads hoisted out of the token loop; no store-ack waits in the tail
# speedup vs baseline: 1.0101x; 1.0017x over previous
.LBB0_2332:
	s_or_b64 exec, exec, s[0:1]
	s_waitcnt lgkmcnt(0)
	s_barrier
	s_movk_i32 s7, 0x2000
	v_ashrrev_i32_e32 v0, 6, v250
	v_add_u32_e32 v66, s96, v0
	v_cmp_gt_i32_e32 vcc, s7, v66
	s_and_saveexec_b64 s[0:1], vcc
	s_cbranch_execz .LBB0_2345
	v_ashrrev_i32_e32 v67, 31, v66
	v_lshlrev_b32_e32 v2, 2, v250
	v_lshlrev_b64 v[0:1], 12, v[66:67]
	v_and_b32_e32 v16, 0xfc, v2
	v_readlane_b32 s12, v253, 6
	v_lshl_add_u64 v[0:1], s[30:31], 0, v[0:1]
	v_mov_b32_e32 v65, 0
	v_lshlrev_b32_e32 v64, 2, v16
	v_readlane_b32 s14, v253, 8
	v_readlane_b32 s15, v253, 9
	v_lshl_add_u64 v[18:19], v[0:1], 0, v[64:65]
	v_and_b32_e32 v135, 15, v250
	v_lshl_add_u64 v[8:9], v[66:67], 2, s[14:15]
	global_load_dwordx4 v[0:3], v[18:19], off
	global_load_dwordx4 v[4:7], v[18:19], off offset:1024
	global_load_dword v67, v[8:9], off
	v_lshl_or_b32 v8, v66, 4, v135
	v_readlane_b32 s16, v253, 10
	v_readlane_b32 s17, v253, 11
	v_ashrrev_i32_e32 v9, 31, v8
	v_readlane_b32 s36, v254, 18
	v_lshl_add_u64 v[20:21], v[8:9], 2, s[16:17]
	global_load_dword v77, v[20:21], off
	global_load_dwordx4 v[8:11], v[18:19], off offset:2048
	global_load_dwordx4 v[12:15], v[18:19], off offset:3072
	v_readlane_b32 s44, v254, 26
	v_readlane_b32 s45, v254, 27
	s_mov_b64 s[16:17], s[44:45]
	v_readlane_b32 s42, v254, 24
	v_readlane_b32 s43, v254, 25
	s_add_u32 s0, s16, 0x3000
	s_mov_b64 s[14:15], s[42:43]
	s_addc_u32 s1, s17, 0
	v_readlane_b32 s21, v253, 15
	s_add_u32 s2, s14, 0x3000
	v_or_b32_e32 v24, 0x100, v16
	v_or_b32_e32 v26, 0x200, v16
	v_or_b32_e32 v28, 0x300, v16
	v_mov_b32_e32 v19, v65
	v_mov_b32_e32 v21, v65
	v_mov_b32_e32 v23, v65
	s_addc_u32 s3, s15, 0
	s_lshl_b32 s21, s92, 2
	v_lshlrev_b32_e32 v18, 2, v24
	v_lshlrev_b32_e32 v20, 2, v26
	v_lshlrev_b32_e32 v22, 2, v28
	v_lshl_add_u64 v[68:69], s[0:1], 0, v[64:65]
	v_lshl_add_u64 v[86:87], s[0:1], 0, v[18:19]
	v_lshl_add_u64 v[90:91], s[0:1], 0, v[20:21]
	v_lshl_add_u64 v[94:95], s[0:1], 0, v[22:23]
	s_add_u32 s0, s14, 0x2000
	s_addc_u32 s1, s15, 0
	v_mbcnt_lo_u32_b32 v17, -1, 0
	v_lshl_add_u64 v[82:83], s[2:3], 0, v[64:65]
	v_lshl_add_u64 v[84:85], s[2:3], 0, v[18:19]
	v_lshl_add_u64 v[88:89], s[2:3], 0, v[20:21]
	v_lshl_add_u64 v[92:93], s[2:3], 0, v[22:23]
	s_add_u32 s2, s16, 0x2000
	v_readlane_b32 s13, v253, 7
	v_readlane_b32 s18, v253, 12
	v_readlane_b32 s19, v253, 13
	v_readlane_b32 s20, v253, 14
	v_mbcnt_hi_u32_b32 v17, -1, v17
	s_addc_u32 s3, s17, 0
	s_mov_b64 s[4:5], 0
	s_movk_i32 s11, 0xfff
	s_movk_i32 s18, 0x1fff
	s_mov_b32 s6, 0x3a800000
	s_mov_b32 s19, 0x800000
	s_movk_i32 s20, 0x6000
	s_mov_b64 s[8:9], 0x5000
	s_mov_b32 s10, 0x3fb504f3
	v_and_b32_e32 v137, 64, v17
	v_lshl_add_u64 v[70:71], s[30:31], 0, v[64:65]
	v_lshl_add_u64 v[72:73], s[12:13], 0, v[64:65]
	v_lshl_add_u64 v[74:75], s[72:73], 0, v[64:65]
	v_lshlrev_b32_e32 v76, 2, v24
	v_lshlrev_b32_e32 v78, 2, v26
	v_lshlrev_b32_e32 v80, 2, v28
	v_lshl_add_u64 v[96:97], s[0:1], 0, v[64:65]
	v_lshl_add_u64 v[98:99], s[0:1], 0, v[18:19]
	v_lshl_add_u64 v[100:101], s[0:1], 0, v[20:21]
	v_lshl_add_u64 v[102:103], s[0:1], 0, v[22:23]
	v_lshl_add_u64 v[104:105], s[2:3], 0, v[64:65]
	v_lshl_add_u64 v[106:107], s[2:3], 0, v[18:19]
	v_lshl_add_u64 v[108:109], s[2:3], 0, v[20:21]
	v_lshl_add_u64 v[110:111], s[2:3], 0, v[22:23]
	v_lshlrev_b32_e32 v64, 2, v16
	v_readlane_b32 s22, v253, 16
	v_readlane_b32 s23, v253, 17
	v_readlane_b32 s24, v253, 18
	v_readlane_b32 s25, v253, 19
	v_readlane_b32 s26, v253, 20
	v_readlane_b32 s27, v253, 21
	v_readlane_b32 s37, v254, 19
	v_readlane_b32 s38, v254, 20
	v_readlane_b32 s39, v254, 21
	s_waitcnt vmcnt(3)
	v_mov_b32_e32 v113, v67
	v_readlane_b32 s40, v254, 22
	v_readlane_b32 s41, v254, 23
	v_readlane_b32 s46, v254, 28
	v_readlane_b32 s47, v254, 29
	s_waitcnt vmcnt(2)
	v_mov_b32_e32 v142, v77
	v_readlane_b32 s48, v254, 30
	v_readlane_b32 s49, v254, 31
	v_readlane_b32 s50, v254, 32
	v_readlane_b32 s51, v254, 33
	global_load_dwordx4 v[172:175], v[84:85], off
	global_load_dwordx4 v[176:179], v[86:87], off
	global_load_dwordx4 v[180:183], v[88:89], off
	global_load_dwordx4 v[184:187], v[90:91], off
	global_load_dwordx4 v[188:191], v[92:93], off
	global_load_dwordx4 v[192:195], v[94:95], off
	s_branch .LBB0_2336

.LBB0_2335:
	s_or_b64 exec, exec, s[12:13]
	v_add_u32_e32 v67, 0xfffff000, v66
	v_lshrrev_b32_e32 v67, 11, v67
	v_readlane_b32 s36, v253, 26
	v_add_u32_e32 v67, 4, v67
	v_readlane_b32 s37, v253, 27
	v_cndmask_b32_e32 v67, 3, v67, vcc
	s_and_b64 s[0:1], exec, s[0:1]
	v_mov_b64_e32 v[138:139], s[36:37]
	s_or_b64 s[4:5], s[0:1], s[4:5]
	v_mad_u64_u32 v[138:139], s[0:1], v67, s20, v[138:139]
	v_lshl_add_u64 v[152:153], v[138:139], 0, s[8:9]
	v_mov_b32_e32 v77, v65
	v_lshl_add_u64 v[138:139], v[152:153], 0, v[64:65]
	v_lshl_add_u64 v[144:145], v[152:153], 0, v[76:77]
	v_mov_b32_e32 v79, v65
	v_mov_b32_e32 v81, v65
	global_load_dwordx4 v[138:141], v[138:139], off
	v_lshl_add_u64 v[148:149], v[152:153], 0, v[78:79]
	global_load_dwordx4 v[144:147], v[144:145], off
	v_lshl_add_u64 v[152:153], v[152:153], 0, v[80:81]
	global_load_dwordx4 v[148:151], v[148:149], off
	v_pk_add_f32 v[160:161], v[114:115], v[116:117]
	global_load_dwordx4 v[152:155], v[152:153], off
	s_nop 0
	global_load_dwordx4 v[114:117], v[82:83], off
	global_load_dwordx4 v[156:159], v[68:69], off
	v_pk_mul_f32 v[160:161], v[160:161], s[6:7] op_sel_hi:[1,0]
	v_readlane_b32 s38, v253, 28
	v_fma_f32 v67, -v161, v161, v160
	v_max_f32_e32 v67, 0, v67
	v_add_f32_e32 v67, 0x3727c5ac, v67
	v_mul_f32_e32 v77, 0x4b800000, v67
	v_cmp_gt_f32_e32 vcc, s19, v67
	v_pk_add_f32 v[0:1], v[0:1], v[160:161] op_sel:[0,1] neg_lo:[0,1] neg_hi:[0,1]
	v_pk_add_f32 v[4:5], v[4:5], v[160:161] op_sel:[0,1] neg_lo:[0,1] neg_hi:[0,1]
	v_cndmask_b32_e32 v67, v67, v77, vcc
	v_rsq_f32_e32 v67, v67
	v_pk_add_f32 v[2:3], v[2:3], v[160:161] op_sel:[0,1] neg_lo:[0,1] neg_hi:[0,1]
	v_pk_add_f32 v[6:7], v[6:7], v[160:161] op_sel:[0,1] neg_lo:[0,1] neg_hi:[0,1]
	v_pk_add_f32 v[8:9], v[8:9], v[160:161] op_sel:[0,1] neg_lo:[0,1] neg_hi:[0,1]
	v_mul_f32_e32 v77, 0x45800000, v67
	v_cndmask_b32_e32 v134, v67, v77, vcc
	v_pk_add_f32 v[12:13], v[12:13], v[160:161] op_sel:[0,1] neg_lo:[0,1] neg_hi:[0,1]
	v_pk_mul_f32 v[0:1], v[0:1], v[134:135] op_sel_hi:[1,0]
	v_pk_mul_f32 v[4:5], v[4:5], v[134:135] op_sel_hi:[1,0]
	v_pk_add_f32 v[10:11], v[10:11], v[160:161] op_sel:[0,1] neg_lo:[0,1] neg_hi:[0,1]
	v_pk_mul_f32 v[2:3], v[2:3], v[134:135] op_sel_hi:[1,0]
	v_pk_mul_f32 v[6:7], v[6:7], v[134:135] op_sel_hi:[1,0]
	v_pk_mul_f32 v[8:9], v[8:9], v[134:135] op_sel_hi:[1,0]
	v_pk_mul_f32 v[12:13], v[12:13], v[134:135] op_sel_hi:[1,0]
	s_waitcnt vmcnt(12)
	v_pk_fma_f32 v[0:1], v[32:33], v[0:1], v[48:49]
	s_waitcnt vmcnt(10)
	v_pk_fma_f32 v[4:5], v[36:37], v[4:5], v[52:53]
	v_pk_mul_f32 v[10:11], v[10:11], v[134:135] op_sel_hi:[1,0]
	v_pk_fma_f32 v[2:3], v[34:35], v[2:3], v[50:51]
	v_pk_fma_f32 v[6:7], v[38:39], v[6:7], v[54:55]
	s_waitcnt vmcnt(8)
	v_pk_fma_f32 v[8:9], v[8:9], v[40:41], v[56:57]
	s_waitcnt vmcnt(6)
	v_pk_fma_f32 v[12:13], v[12:13], v[44:45], v[60:61]
	v_pk_fma_f32 v[10:11], v[10:11], v[42:43], v[58:59]
	v_pk_add_f32 v[14:15], v[14:15], v[160:161] op_sel:[0,1] neg_lo:[0,1] neg_hi:[0,1]
	v_ashrrev_i32_e32 v67, 31, v66
	v_pk_mul_f32 v[14:15], v[14:15], v[134:135] op_sel_hi:[1,0]
	v_mov_b32_e32 v77, v142
	v_pk_fma_f32 v[14:15], v[14:15], v[46:47], v[62:63]
	v_readlane_b32 s39, v253, 29
	v_readlane_b32 s40, v253, 30
	v_readlane_b32 s41, v253, 31
	v_readlane_b32 s42, v253, 32
	v_readlane_b32 s43, v253, 33
	v_readlane_b32 s44, v253, 34
	v_readlane_b32 s45, v253, 35
	v_readlane_b32 s46, v253, 36
	v_readlane_b32 s47, v253, 37
	v_readlane_b32 s48, v253, 38
	v_readlane_b32 s49, v253, 39
	v_readlane_b32 s50, v253, 40
	v_readlane_b32 s51, v253, 41
	s_waitcnt vmcnt(5)
	v_pk_mul_f32 v[32:33], v[124:125], v[138:139]
	v_pk_mul_f32 v[34:35], v[132:133], v[140:141]
	s_waitcnt vmcnt(4)
	v_pk_mul_f32 v[36:37], v[130:131], v[144:145]
	v_pk_mul_f32 v[38:39], v[128:129], v[146:147]
	s_waitcnt vmcnt(3)
	v_pk_mul_f32 v[40:41], v[126:127], v[148:149]
	v_pk_fma_f32 v[0:1], v[0:1], s[10:11], v[32:33] op_sel_hi:[1,0,1]
	s_waitcnt vmcnt(2)
	v_pk_mul_f32 v[44:45], v[120:121], v[152:153]
	v_pk_fma_f32 v[32:33], v[4:5], s[10:11], v[36:37] op_sel_hi:[1,0,1]
	v_pk_mul_f32 v[42:43], v[122:123], v[150:151]
	v_pk_fma_f32 v[2:3], v[2:3], s[10:11], v[34:35] op_sel_hi:[1,0,1]
	v_pk_fma_f32 v[34:35], v[6:7], s[10:11], v[38:39] op_sel_hi:[1,0,1]
	v_pk_fma_f32 v[8:9], v[8:9], s[10:11], v[40:41] op_sel_hi:[1,0,1]
	v_pk_fma_f32 v[40:41], v[12:13], s[10:11], v[44:45] op_sel_hi:[1,0,1]
	v_pk_mul_f32 v[4:5], v[0:1], v[0:1]
	v_pk_mul_f32 v[12:13], v[32:33], v[32:33]
	v_pk_fma_f32 v[10:11], v[10:11], s[10:11], v[42:43] op_sel_hi:[1,0,1]
	v_pk_mul_f32 v[6:7], v[2:3], v[2:3]
	v_pk_mul_f32 v[36:37], v[34:35], v[34:35]
	v_pk_mul_f32 v[38:39], v[8:9], v[8:9]
	v_add_f32_e32 v12, v12, v13
	v_add_f32_e32 v4, v4, v5
	v_add_f32_e32 v48, v0, v1
	v_pk_mul_f32 v[42:43], v[10:11], v[10:11]
	v_add_f32_e32 v12, v12, v36
	v_add_f32_e32 v4, v4, v6
	v_add_f32_e32 v5, v38, v39
	v_pk_mul_f32 v[46:47], v[118:119], v[154:155]
	v_add_f32_e32 v49, v32, v33
	v_add_f32_e32 v48, v48, v2
	v_add_f32_e32 v12, v12, v37
	v_add_f32_e32 v4, v4, v7
	v_add_f32_e32 v5, v5, v42
	v_pk_fma_f32 v[14:15], v[14:15], s[10:11], v[46:47] op_sel_hi:[1,0,1]
	v_add_f32_e32 v50, v8, v9
	v_pk_mul_f32 v[44:45], v[40:41], v[40:41]
	v_add_f32_e32 v49, v49, v34
	v_add_f32_e32 v13, v48, v3
	v_add_f32_e32 v4, v4, v12
	v_add_f32_e32 v5, v5, v43
	v_pk_mul_f32 v[46:47], v[14:15], v[14:15]
	v_add_f32_e32 v51, v40, v41
	v_add_f32_e32 v50, v50, v10
	v_add_f32_e32 v48, v49, v35
	v_add_f32_e32 v13, 0, v13
	v_add_f32_e32 v4, v4, v5
	v_add_f32_e32 v5, v44, v45
	v_add_f32_e32 v51, v51, v14
	v_add_f32_e32 v49, v50, v11
	v_add_f32_e32 v13, v13, v48
	v_add_f32_e32 v5, v5, v46
	v_add_f32_e32 v50, v51, v15
	v_add_f32_e32 v13, v13, v49
	v_add_f32_e32 v5, v5, v47
	v_add_f32_e32 v4, v4, v5
	v_add_f32_e32 v5, v13, v50
	s_nop 0
	v_add_f32_dpp v4, v4, v4 row_ror:8 row_mask:0xf bank_mask:0xf bound_ctrl:1
	v_add_f32_dpp v5, v5, v5 row_ror:8 row_mask:0xf bank_mask:0xf bound_ctrl:1
	s_nop 0
	v_add_f32_dpp v4, v4, v4 row_ror:4 row_mask:0xf bank_mask:0xf bound_ctrl:1
	v_add_f32_dpp v5, v5, v5 row_ror:4 row_mask:0xf bank_mask:0xf bound_ctrl:1
	s_nop 0
	v_add_f32_dpp v4, v4, v4 row_ror:2 row_mask:0xf bank_mask:0xf bound_ctrl:1
	v_add_f32_dpp v5, v5, v5 row_ror:2 row_mask:0xf bank_mask:0xf bound_ctrl:1
	s_nop 0
	v_add_f32_dpp v4, v4, v4 row_ror:1 row_mask:0xf bank_mask:0xf bound_ctrl:1
	v_add_f32_dpp v5, v5, v5 row_ror:1 row_mask:0xf bank_mask:0xf bound_ctrl:1
	v_mov_b32_e32 v6, v5
	s_nop 1
	v_permlane16_swap_b32_e32 v5, v6
	v_add_f32_e32 v5, v5, v6
	v_mov_b32_e32 v6, v4
	s_nop 1
	v_permlane16_swap_b32_e32 v4, v6
	v_add_f32_e32 v4, v4, v6
	v_mov_b32_e32 v7, v5
	v_mov_b32_e32 v6, v4
	s_nop 0
	v_permlane32_swap_b32_e32 v5, v7
	v_permlane32_swap_b32_e32 v4, v6
	v_pk_add_f32 v[4:5], v[4:5], v[6:7]
	s_nop 0
	v_pk_mul_f32 v[42:43], v[4:5], s[6:7] op_sel_hi:[1,0]
	s_nop 0
	v_fma_f32 v4, -v43, v43, v42
	v_max_f32_e32 v4, 0, v4
	v_add_f32_e32 v4, 0x3727c5ac, v4
	v_mul_f32_e32 v5, 0x4b800000, v4
	v_cmp_gt_f32_e32 vcc, s19, v4
	v_pk_add_f32 v[0:1], v[0:1], v[42:43] op_sel:[0,1] neg_lo:[0,1] neg_hi:[0,1]
	v_pk_add_f32 v[2:3], v[2:3], v[42:43] op_sel:[0,1] neg_lo:[0,1] neg_hi:[0,1]
	v_cndmask_b32_e32 v4, v4, v5, vcc
	v_rsq_f32_e32 v6, v4
	v_lshlrev_b64 v[4:5], 12, v[66:67]
	v_lshl_add_u64 v[44:45], v[74:75], 0, v[4:5]
	v_pk_add_f32 v[12:13], v[32:33], v[42:43] op_sel:[0,1] neg_lo:[0,1] neg_hi:[0,1]
	v_mul_f32_e32 v4, 0x45800000, v6
	v_cndmask_b32_e32 v46, v6, v4, vcc
	v_pk_mul_f32 v[0:1], v[0:1], v[46:47] op_sel_hi:[1,0]
	v_pk_mul_f32 v[2:3], v[2:3], v[46:47] op_sel_hi:[1,0]
	s_waitcnt vmcnt(0)
	v_pk_fma_f32 v[0:1], v[114:115], v[0:1], v[156:157]
	v_pk_fma_f32 v[2:3], v[116:117], v[2:3], v[158:159]
	global_store_dwordx4 v[44:45], v[0:3], off
	s_nop 1
	v_pk_add_f32 v[32:33], v[34:35], v[42:43] op_sel:[0,1] neg_lo:[0,1] neg_hi:[0,1]
	v_pk_mul_f32 v[12:13], v[12:13], v[46:47] op_sel_hi:[1,0]
	v_pk_mul_f32 v[32:33], v[32:33], v[46:47] op_sel_hi:[1,0]
	v_pk_add_f32 v[8:9], v[8:9], v[42:43] op_sel:[0,1] neg_lo:[0,1] neg_hi:[0,1]
	v_pk_add_f32 v[10:11], v[10:11], v[42:43] op_sel:[0,1] neg_lo:[0,1] neg_hi:[0,1]
	v_pk_mul_f32 v[8:9], v[8:9], v[46:47] op_sel_hi:[1,0]
	v_pk_mul_f32 v[10:11], v[10:11], v[46:47] op_sel_hi:[1,0]
	v_pk_add_f32 v[14:15], v[14:15], v[42:43] op_sel:[0,1] neg_lo:[0,1] neg_hi:[0,1]
	v_mov_b32_e32 v67, v113
	v_mov_b32_e32 v66, v112
	v_pk_fma_f32 v[0:1], v[12:13], v[172:173], v[176:177]
	v_pk_fma_f32 v[2:3], v[32:33], v[174:175], v[178:179]
	global_store_dwordx4 v[44:45], v[0:3], off offset:1024
	s_nop 1
	v_mov_b64_e32 v[12:13], v[20:21]
	v_pk_fma_f32 v[0:1], v[8:9], v[180:181], v[184:185]
	v_pk_fma_f32 v[2:3], v[10:11], v[182:183], v[186:187]
	global_store_dwordx4 v[44:45], v[0:3], off offset:2048
	s_nop 1
	v_mov_b64_e32 v[0:1], v[16:17]
	v_pk_add_f32 v[16:17], v[40:41], v[42:43] op_sel:[0,1] neg_lo:[0,1] neg_hi:[0,1]
	v_mov_b64_e32 v[2:3], v[18:19]
	v_pk_mul_f32 v[16:17], v[16:17], v[46:47] op_sel_hi:[1,0]
	v_pk_mul_f32 v[18:19], v[14:15], v[46:47] op_sel_hi:[1,0]
	v_mov_b64_e32 v[4:5], v[24:25]
	v_mov_b64_e32 v[6:7], v[26:27]
	v_mov_b64_e32 v[8:9], v[28:29]
	v_mov_b64_e32 v[10:11], v[30:31]
	v_pk_fma_f32 v[14:15], v[16:17], v[188:189], v[192:193]
	v_pk_fma_f32 v[16:17], v[18:19], v[190:191], v[194:195]
	global_store_dwordx4 v[44:45], v[14:17], off offset:3072
	s_nop 1
	v_mov_b64_e32 v[14:15], v[22:23]
	s_andn2_b64 exec, exec, s[4:5]
	s_cbranch_execz .LBB0_2345
